# moba past-block step: 16 V-fragment LDS transpose reads hoisted ahead of softmax, PV MFMAs behind counted lgkmcnt waits
# speedup vs baseline: 1.0141x; 1.0013x over previous
.LBB0_432:
	v_mov_b32_e32 v90, v197
	s_nop 0
	v_and_b32_e32 v36, 15, v90
	v_bfe_u32 v91, v90, 4, 2
	v_mul_u32_u24_e32 v36, 0x90, v36
	v_lshl_add_u32 v98, v91, 4, v36
	ds_read_b128 v[36:39], v98
	ds_read_b128 v[86:89], v98 offset:64
	ds_read_b128 v[78:81], v98 offset:4608
	ds_read_b128 v[94:97], v98 offset:4672
	ds_read_b128 v[40:43], v98 offset:2304
	ds_read_b128 v[82:85], v98 offset:6912
	s_waitcnt lgkmcnt(5)
	v_mfma_f32_16x16x32_bf16 v[36:39], v[36:39], v[44:47], 0
	s_waitcnt lgkmcnt(3)
	v_mfma_f32_16x16x32_bf16 v[78:81], v[78:81], v[44:47], 0
	v_mfma_f32_16x16x32_bf16 v[86:89], v[86:89], v[48:51], v[36:39]
	s_nop 4
	ds_read_b128 v[36:39], v98 offset:2368
	s_waitcnt lgkmcnt(3)
	v_mfma_f32_16x16x32_bf16 v[78:81], v[94:97], v[48:51], v[78:81]
	ds_read_b128 v[94:97], v98 offset:6976
	s_waitcnt lgkmcnt(3)
	v_mfma_f32_16x16x32_bf16 v[40:43], v[40:43], v[44:47], 0
	s_waitcnt lgkmcnt(2)
	v_mfma_f32_16x16x32_bf16 v[82:85], v[82:85], v[44:47], 0
	s_waitcnt lgkmcnt(1)
	v_mfma_f32_16x16x32_bf16 v[38:41], v[36:39], v[48:51], v[40:43]
	v_max_f32_e32 v36, v89, v89
	v_max_f32_e32 v37, v88, v88
	v_max_f32_e32 v36, v37, v36
	s_waitcnt lgkmcnt(0)
	v_mfma_f32_16x16x32_bf16 v[82:85], v[94:97], v[48:51], v[82:85]
	v_bfe_u32 v186, v90, 2, 2
	v_lshlrev_b32_e32 v187, 3, v90
	v_lshl_or_b32 v186, v91, 2, v186
	v_and_b32_e32 v187, 24, v187
	v_mad_u32_u24 v186, v186, s0, v187
	ds_read_b64_tr_b16 v[154:155], v186 offset:9216
	ds_read_b64_tr_b16 v[156:157], v186 offset:11520
	ds_read_b64_tr_b16 v[158:159], v186 offset:9248
	ds_read_b64_tr_b16 v[160:161], v186 offset:11552
	ds_read_b64_tr_b16 v[162:163], v186 offset:9280
	ds_read_b64_tr_b16 v[164:165], v186 offset:11584
	ds_read_b64_tr_b16 v[166:167], v186 offset:9312
	ds_read_b64_tr_b16 v[168:169], v186 offset:11616
	ds_read_b64_tr_b16 v[170:171], v186 offset:13824
	ds_read_b64_tr_b16 v[172:173], v186 offset:16128
	ds_read_b64_tr_b16 v[174:175], v186 offset:13856
	ds_read_b64_tr_b16 v[176:177], v186 offset:16160
	ds_read_b64_tr_b16 v[178:179], v186 offset:13888
	ds_read_b64_tr_b16 v[180:181], v186 offset:16192
	ds_read_b64_tr_b16 v[182:183], v186 offset:13920
	ds_read_b64_tr_b16 v[184:185], v186 offset:16224
	v_max3_f32 v36, v86, v87, v36
	s_nop 1
	v_max_f32_e32 v37, v41, v41
	v_max_f32_e32 v42, v40, v40
	v_max_f32_e32 v37, v42, v37
	v_max3_f32 v37, v38, v39, v37
	v_max3_f32 v36, v36, s28, v37
	v_max_f32_e32 v37, v81, v81
	v_max_f32_e32 v42, v80, v80
	v_max_f32_e32 v37, v42, v37
	v_max_f32_e32 v42, v85, v85
	v_max_f32_e32 v43, v84, v84
	v_max_f32_e32 v42, v43, v42
	v_max3_f32 v37, v78, v79, v37
	v_max3_f32 v42, v82, v83, v42
	v_max3_f32 v36, v36, v37, v42
	v_mov_b32_e32 v37, v36
	s_nop 1
	v_permlane16_swap_b32_e32 v36, v37
	v_max_f32_e32 v37, v37, v37
	v_max_f32_e32 v36, v36, v36
	v_max_f32_e32 v36, v36, v37
	v_mov_b32_e32 v37, v36
	s_nop 1
	v_permlane32_swap_b32_e32 v36, v37
	v_max3_f32 v37, v17, v36, v37
	v_mul_f32_e32 v36, 0x3e38aa3b, v37
	v_cmp_ngt_f32_e32 vcc, s36, v37
	v_sub_f32_e32 v17, v17, v37
	v_mul_f32_e32 v17, 0x3e38aa3b, v17
	v_cndmask_b32_e32 v36, 0, v36, vcc
	v_fma_f32 v42, v86, s29, -v36
	v_exp_f32_e32 v86, v42
	v_fma_f32 v43, v87, s29, -v36
	v_exp_f32_e32 v87, v43
	v_fma_f32 v43, v88, s29, -v36
	v_exp_f32_e32 v88, v43
	v_fma_f32 v43, v89, s29, -v36
	v_exp_f32_e32 v89, v43
	v_fma_f32 v38, v38, s29, -v36
	v_add_f32_e32 v42, 0, v86
	v_exp_f32_e32 v94, v38
	v_fma_f32 v39, v39, s29, -v36
	v_add_f32_e32 v42, v87, v42
	v_exp_f32_e32 v39, v39
	v_fma_f32 v40, v40, s29, -v36
	v_add_f32_e32 v42, v88, v42
	v_exp_f32_e32 v95, v40
	v_fma_f32 v40, v41, s29, -v36
	v_add_f32_e32 v42, v89, v42
	v_exp_f32_e32 v96, v40
	v_fma_f32 v40, v78, s29, -v36
	v_add_f32_e32 v38, v94, v42
	v_exp_f32_e32 v97, v40
	v_fma_f32 v40, v79, s29, -v36
	v_add_f32_e32 v38, v39, v38
	v_exp_f32_e32 v98, v40
	v_fma_f32 v40, v80, s29, -v36
	v_add_f32_e32 v38, v95, v38
	v_exp_f32_e32 v99, v40
	v_fma_f32 v40, v81, s29, -v36
	v_add_f32_e32 v38, v96, v38
	v_exp_f32_e32 v100, v40
	v_fma_f32 v40, v82, s29, -v36
	v_add_f32_e32 v38, v97, v38
	v_exp_f32_e32 v101, v40
	v_fma_f32 v40, v83, s29, -v36
	v_add_f32_e32 v38, v98, v38
	v_exp_f32_e32 v102, v40
	v_fma_f32 v40, v84, s29, -v36
	v_add_f32_e32 v38, v99, v38
	v_exp_f32_e32 v103, v40
	v_fma_f32 v36, v85, s29, -v36
	v_add_f32_e32 v38, v100, v38
	v_exp_f32_e32 v104, v36
	v_add_f32_e32 v38, v101, v38
	v_exp_f32_e32 v36, v17
	v_add_f32_e32 v38, v102, v38
	v_add_f32_e32 v38, v103, v38
	v_add_f32_e32 v38, v104, v38
	v_fmac_f32_e32 v38, v16, v36
	v_pk_mul_f32 v[42:43], v[62:63], v[36:37] op_sel_hi:[1,0]
	v_pk_mul_f32 v[40:41], v[60:61], v[36:37] op_sel_hi:[1,0]
	v_pk_mul_f32 v[62:63], v[66:67], v[36:37] op_sel_hi:[1,0]
	v_pk_mul_f32 v[60:61], v[64:65], v[36:37] op_sel_hi:[1,0]
	v_pk_mul_f32 v[66:67], v[70:71], v[36:37] op_sel_hi:[1,0]
	v_pk_mul_f32 v[64:65], v[68:69], v[36:37] op_sel_hi:[1,0]
	v_pk_mul_f32 v[70:71], v[74:75], v[36:37] op_sel_hi:[1,0]
	v_pk_mul_f32 v[68:69], v[72:73], v[36:37] op_sel_hi:[1,0]
	v_cvt_pk_bf16_f32 v72, v86, v87
	v_cvt_pk_bf16_f32 v73, v88, v89
	v_cvt_pk_bf16_f32 v74, v94, v39
	v_cvt_pk_bf16_f32 v75, v95, v96
	v_cvt_pk_bf16_f32 v86, v97, v98
	v_cvt_pk_bf16_f32 v87, v99, v100
	v_cvt_pk_bf16_f32 v88, v101, v102
	v_cvt_pk_bf16_f32 v89, v103, v104
	v_cmp_ne_u32_e32 vcc, 3, v77
	s_waitcnt lgkmcnt(14)
	v_mfma_f32_16x16x32_bf16 v[40:43], v[154:157], v[72:75], v[40:43]
	s_waitcnt lgkmcnt(12)
	v_mfma_f32_16x16x32_bf16 v[78:81], v[158:161], v[72:75], v[60:63]
	s_and_b64 vcc, exec, vcc
	s_waitcnt lgkmcnt(10)
	v_mfma_f32_16x16x32_bf16 v[82:85], v[162:165], v[72:75], v[64:67]
	s_waitcnt lgkmcnt(8)
	v_mfma_f32_16x16x32_bf16 v[72:75], v[166:169], v[72:75], v[68:71]
	s_waitcnt lgkmcnt(6)
	v_mfma_f32_16x16x32_bf16 v[60:63], v[170:173], v[86:89], v[40:43]
	s_waitcnt lgkmcnt(4)
	v_mfma_f32_16x16x32_bf16 v[64:67], v[174:177], v[86:89], v[78:81]
	s_waitcnt lgkmcnt(2)
	v_mfma_f32_16x16x32_bf16 v[68:71], v[178:181], v[86:89], v[82:85]
	s_waitcnt lgkmcnt(0)
	v_mfma_f32_16x16x32_bf16 v[72:75], v[182:185], v[86:89], v[72:75]
	s_cbranch_vccnz .LBB0_421
	v_mov_b32_e32 v16, v38
	v_mov_b32_e32 v17, v38
	s_nop 1
	v_permlane16_swap_b32_e32 v16, v17
	v_add_f32_e32 v39, v16, v17
	v_mov_b32_e32 v40, v39
	s_nop 1
	v_permlane32_swap_b32_e32 v39, v40
	s_and_saveexec_b64 s[10:11], s[42:43]
	s_cbranch_execz .LBB0_420
	v_lshlrev_b32_e32 v41, 2, v1
	ds_read2st64_b32 v[16:17], v41 offset0:208 offset1:210
	v_max_f32_e32 v42, v37, v37
	s_movk_i32 s17, 0x110
	v_mad_u64_u32 v[82:83], s[20:21], v1, s17, v[4:5]
	s_waitcnt lgkmcnt(0)
	v_max_f32_e32 v36, v16, v16
	v_max_f32_e32 v42, v36, v42
	v_sub_f32_e32 v36, v37, v42
	v_sub_f32_e32 v16, v16, v42
	v_mul_f32_e32 v36, 0x3e38aa3b, v36
	v_mul_f32_e32 v16, 0x3e38aa3b, v16
	v_exp_f32_e32 v36, v36
	ds_read_b128 v[78:81], v82 offset:18432
	v_exp_f32_e32 v16, v16
	v_pk_mul_f32 v[84:85], v[62:63], v[36:37] op_sel_hi:[1,0]
	v_pk_mul_f32 v[86:87], v[60:61], v[36:37] op_sel_hi:[1,0]
	s_waitcnt lgkmcnt(0)
	v_pk_fma_f32 v[80:81], v[80:81], v[16:17], v[84:85] op_sel_hi:[1,0,1]
	v_pk_fma_f32 v[78:79], v[78:79], v[16:17], v[86:87] op_sel_hi:[1,0,1]
	ds_write_b128 v82, v[78:81] offset:18432
	ds_read_b128 v[78:81], v82 offset:18496
	v_pk_mul_f32 v[84:85], v[66:67], v[36:37] op_sel_hi:[1,0]
	v_pk_mul_f32 v[86:87], v[64:65], v[36:37] op_sel_hi:[1,0]
	s_waitcnt lgkmcnt(0)
	v_pk_fma_f32 v[80:81], v[80:81], v[16:17], v[84:85] op_sel_hi:[1,0,1]
	v_pk_fma_f32 v[78:79], v[78:79], v[16:17], v[86:87] op_sel_hi:[1,0,1]
	ds_write_b128 v82, v[78:81] offset:18496
	ds_read_b128 v[78:81], v82 offset:18560
	v_pk_mul_f32 v[84:85], v[70:71], v[36:37] op_sel_hi:[1,0]
	v_pk_mul_f32 v[86:87], v[68:69], v[36:37] op_sel_hi:[1,0]
	s_waitcnt lgkmcnt(0)
	v_pk_fma_f32 v[80:81], v[16:17], v[80:81], v[84:85] op_sel_hi:[0,1,1]
	v_pk_fma_f32 v[78:79], v[16:17], v[78:79], v[86:87] op_sel_hi:[0,1,1]
	ds_write_b128 v82, v[78:81] offset:18560
	ds_read_b128 v[78:81], v82 offset:18624
	s_waitcnt lgkmcnt(0)
	v_pk_mul_f32 v[80:81], v[16:17], v[80:81] op_sel_hi:[0,1]
	v_pk_mul_f32 v[78:79], v[16:17], v[78:79] op_sel_hi:[0,1]
	v_pk_fma_f32 v[80:81], v[74:75], v[36:37], v[80:81] op_sel_hi:[1,0,1]
	v_pk_fma_f32 v[78:79], v[72:73], v[36:37], v[78:79] op_sel_hi:[1,0,1]
	ds_write_b128 v82, v[78:81] offset:18624
	s_and_b64 exec, exec, s[38:39]
	s_cbranch_execz .LBB0_420
	v_add_f32_e32 v39, v39, v40
	v_mul_f32_e32 v36, v39, v36
	v_fmac_f32_e32 v36, v17, v16
	ds_write2st64_b32 v41, v42, v36 offset0:208 offset1:210
	s_branch .LBB0_420
